# weight transposes: lane-to-k mapping changed so each store writes 128 contiguous bytes, stores written through (sc1): bf16 weights no longer sit dirty in L2
# speedup vs baseline: 1.0092x; 1.0044x over previous
.Lptr_kdone:
	v_lshrrev_b32_e32 v112, 4, v1
	v_and_b32_e32 v113, 15, v1
	v_lshlrev_b32_e32 v113, 4, v113
	v_mul_u32_u24_e32 v114, 0x104, v112
	v_add_u32_e32 v114, v114, v113
	v_lshrrev_b32_e32 v116, 3, v1
	v_and_b32_e32 v117, 7, v1
	v_mul_u32_u24_e32 v115, 0x820, v117
	v_lshl_add_u32 v115, v116, 2, v115
	v_lshlrev_b32_e32 v117, 4, v117
	s_mul_i32 s48, s81, 0
	s_add_u32 s48, s48, s39
	s_min_u32 s48, s48, s84
	s_sub_u32 s0, s48, 0x80
	s_cmpk_lt_u32 s0, 0x80
	s_cbranch_scc1 .Lptr_dec1_br
	s_cmpk_lt_u32 s0, 0x100
	s_cbranch_scc1 .Lptr_dec1_out
	s_cmpk_lt_u32 s0, 0x3c0
	s_cbranch_scc1 .Lptr_dec1_up
	s_sub_u32 s0, s0, 0x3c0
	s_lshr_b32 s2, s0, 4
	s_and_b32 s3, s0, 15
	s_lshl_b32 s12, s2, 19
	s_lshl_b32 s13, s3, 8
	s_add_u32 s12, s12, s13
	s_add_u32 s30, s21, s12
	s_addc_u32 s31, s68, 0
	s_mul_i32 s12, s3, 0x58000
	s_lshl_b32 s13, s2, 8
	s_add_u32 s12, s12, s13
	s_add_u32 s74, s6, s12
	s_addc_u32 s75, s7, 0
	s_movk_i32 s76, 0x1000
	s_movk_i32 s86, 0x1600
	s_branch .Lptr_dec1_done

.Lptr_dec4_done:
	v_mul_lo_u32 v123, v112, s76
	v_add_u32_e32 v118, v123, v113
	s_lshl_b32 vcc_lo, s76, 5
	v_add_u32_e32 v119, vcc_lo, v118
	v_add_u32_e32 v120, vcc_lo, v119
	v_add_u32_e32 v121, vcc_lo, v120
	global_load_dwordx4 v[124:127], v118, s[30:31] nt
	global_load_dwordx4 v[128:131], v119, s[30:31] nt
	global_load_dwordx4 v[132:135], v120, s[30:31] nt
	global_load_dwordx4 v[136:139], v121, s[30:31] nt
	s_waitcnt vmcnt(12)
	ds_write_b32 v114, v40 offset:0
	ds_write_b32 v114, v41 offset:4
	ds_write_b32 v114, v42 offset:8
	ds_write_b32 v114, v43 offset:12
	ds_write_b32 v114, v44 offset:8320
	ds_write_b32 v114, v45 offset:8324
	ds_write_b32 v114, v46 offset:8328
	ds_write_b32 v114, v47 offset:8332
	ds_write_b32 v114, v48 offset:16640
	ds_write_b32 v114, v49 offset:16644
	ds_write_b32 v114, v50 offset:16648
	ds_write_b32 v114, v51 offset:16652
	ds_write_b32 v114, v52 offset:24960
	ds_write_b32 v114, v53 offset:24964
	ds_write_b32 v114, v54 offset:24968
	ds_write_b32 v114, v55 offset:24972
	s_waitcnt lgkmcnt(0)
	s_barrier
	ds_read_b32 v88, v115 offset:0
	ds_read_b32 v89, v115 offset:260
	ds_read_b32 v90, v115 offset:520
	ds_read_b32 v91, v115 offset:780
	ds_read_b32 v92, v115 offset:1040
	ds_read_b32 v93, v115 offset:1300
	ds_read_b32 v94, v115 offset:1560
	ds_read_b32 v95, v115 offset:1820
	ds_read_b32 v96, v115 offset:16640
	ds_read_b32 v97, v115 offset:16900
	ds_read_b32 v98, v115 offset:17160
	ds_read_b32 v99, v115 offset:17420
	ds_read_b32 v100, v115 offset:17680
	ds_read_b32 v101, v115 offset:17940
	ds_read_b32 v102, v115 offset:18200
	ds_read_b32 v103, v115 offset:18460
	s_mul_i32 s48, s81, 0
	s_add_u32 s48, s48, s39
	s_min_u32 s48, s48, s84
	s_sub_u32 s0, s48, 0x80
	s_cmpk_lt_u32 s0, 0x80
	s_cbranch_scc1 .Lptr_dec5_br
	s_cmpk_lt_u32 s0, 0x100
	s_cbranch_scc1 .Lptr_dec5_out
	s_cmpk_lt_u32 s0, 0x3c0
	s_cbranch_scc1 .Lptr_dec5_up
	s_sub_u32 s0, s0, 0x3c0
	s_lshr_b32 s2, s0, 4
	s_and_b32 s3, s0, 15
	s_lshl_b32 s12, s2, 19
	s_lshl_b32 s13, s3, 8
	s_add_u32 s12, s12, s13
	s_add_u32 s30, s21, s12
	s_addc_u32 s31, s68, 0
	s_mul_i32 s12, s3, 0x58000
	s_lshl_b32 s13, s2, 8
	s_add_u32 s12, s12, s13
	s_add_u32 s74, s6, s12
	s_addc_u32 s75, s7, 0
	s_movk_i32 s76, 0x1000
	s_movk_i32 s86, 0x1600
	s_branch .Lptr_dec5_done

.Lptr_dec5_done:
	v_mul_lo_u32 v122, v116, s86
	v_add_u32_e32 v122, v122, v117
	s_waitcnt lgkmcnt(0)
	v_cvt_pk_bf16_f32 v104, v88, v89
	v_cvt_pk_bf16_f32 v105, v90, v91
	v_cvt_pk_bf16_f32 v106, v92, v93
	v_cvt_pk_bf16_f32 v107, v94, v95
	v_cvt_pk_bf16_f32 v108, v96, v97
	v_cvt_pk_bf16_f32 v109, v98, v99
	v_cvt_pk_bf16_f32 v110, v100, v101
	v_cvt_pk_bf16_f32 v111, v102, v103
	global_store_dwordx4 v122, v[104:107], s[74:75] sc1
	global_store_dwordx4 v122, v[108:111], s[74:75] offset:128 sc1
	s_nop 1
	s_mul_i32 s48, s81, 4
	s_add_u32 s48, s48, s39
	s_min_u32 s48, s48, s84
	s_sub_u32 s0, s48, 0x80
	s_cmpk_lt_u32 s0, 0x80
	s_cbranch_scc1 .Lptr_dec6_br
	s_cmpk_lt_u32 s0, 0x100
	s_cbranch_scc1 .Lptr_dec6_out
	s_cmpk_lt_u32 s0, 0x3c0
	s_cbranch_scc1 .Lptr_dec6_up
	s_sub_u32 s0, s0, 0x3c0
	s_lshr_b32 s2, s0, 4
	s_and_b32 s3, s0, 15
	s_lshl_b32 s12, s2, 19
	s_lshl_b32 s13, s3, 8
	s_add_u32 s12, s12, s13
	s_add_u32 s30, s21, s12
	s_addc_u32 s31, s68, 0
	s_mul_i32 s12, s3, 0x58000
	s_lshl_b32 s13, s2, 8
	s_add_u32 s12, s12, s13
	s_add_u32 s74, s6, s12
	s_addc_u32 s75, s7, 0
	s_movk_i32 s76, 0x1000
	s_movk_i32 s86, 0x1600
	s_branch .Lptr_dec6_done

.Lptr_dec6_done:
	v_mul_lo_u32 v123, v112, s76
	v_add_u32_e32 v118, v123, v113
	s_lshl_b32 vcc_lo, s76, 5
	v_add_u32_e32 v119, vcc_lo, v118
	v_add_u32_e32 v120, vcc_lo, v119
	v_add_u32_e32 v121, vcc_lo, v120
	global_load_dwordx4 v[40:43], v118, s[30:31] nt
	global_load_dwordx4 v[44:47], v119, s[30:31] nt
	global_load_dwordx4 v[48:51], v120, s[30:31] nt
	global_load_dwordx4 v[52:55], v121, s[30:31] nt
	s_waitcnt vmcnt(14)
	ds_write_b32 v114, v56 offset:33792
	ds_write_b32 v114, v57 offset:33796
	ds_write_b32 v114, v58 offset:33800
	ds_write_b32 v114, v59 offset:33804
	ds_write_b32 v114, v60 offset:42112
	ds_write_b32 v114, v61 offset:42116
	ds_write_b32 v114, v62 offset:42120
	ds_write_b32 v114, v63 offset:42124
	ds_write_b32 v114, v64 offset:50432
	ds_write_b32 v114, v65 offset:50436
	ds_write_b32 v114, v66 offset:50440
	ds_write_b32 v114, v67 offset:50444
	ds_write_b32 v114, v68 offset:58752
	ds_write_b32 v114, v69 offset:58756
	ds_write_b32 v114, v70 offset:58760
	ds_write_b32 v114, v71 offset:58764
	s_waitcnt lgkmcnt(0)
	s_barrier
	ds_read_b32 v88, v115 offset:33792
	ds_read_b32 v89, v115 offset:34052
	ds_read_b32 v90, v115 offset:34312
	ds_read_b32 v91, v115 offset:34572
	ds_read_b32 v92, v115 offset:34832
	ds_read_b32 v93, v115 offset:35092
	ds_read_b32 v94, v115 offset:35352
	ds_read_b32 v95, v115 offset:35612
	ds_read_b32 v96, v115 offset:50432
	ds_read_b32 v97, v115 offset:50692
	ds_read_b32 v98, v115 offset:50952
	ds_read_b32 v99, v115 offset:51212
	ds_read_b32 v100, v115 offset:51472
	ds_read_b32 v101, v115 offset:51732
	ds_read_b32 v102, v115 offset:51992
	ds_read_b32 v103, v115 offset:52252
	s_mul_i32 s48, s81, 1
	s_add_u32 s48, s48, s39
	s_min_u32 s48, s48, s84
	s_sub_u32 s0, s48, 0x80
	s_cmpk_lt_u32 s0, 0x80
	s_cbranch_scc1 .Lptr_dec7_br
	s_cmpk_lt_u32 s0, 0x100
	s_cbranch_scc1 .Lptr_dec7_out
	s_cmpk_lt_u32 s0, 0x3c0
	s_cbranch_scc1 .Lptr_dec7_up
	s_sub_u32 s0, s0, 0x3c0
	s_lshr_b32 s2, s0, 4
	s_and_b32 s3, s0, 15
	s_lshl_b32 s12, s2, 19
	s_lshl_b32 s13, s3, 8
	s_add_u32 s12, s12, s13
	s_add_u32 s30, s21, s12
	s_addc_u32 s31, s68, 0
	s_mul_i32 s12, s3, 0x58000
	s_lshl_b32 s13, s2, 8
	s_add_u32 s12, s12, s13
	s_add_u32 s74, s6, s12
	s_addc_u32 s75, s7, 0
	s_movk_i32 s76, 0x1000
	s_movk_i32 s86, 0x1600
	s_branch .Lptr_dec7_done

.Lptr_dec7_done:
	v_mul_lo_u32 v122, v116, s86
	v_add_u32_e32 v122, v122, v117
	s_waitcnt lgkmcnt(0)
	v_cvt_pk_bf16_f32 v104, v88, v89
	v_cvt_pk_bf16_f32 v105, v90, v91
	v_cvt_pk_bf16_f32 v106, v92, v93
	v_cvt_pk_bf16_f32 v107, v94, v95
	v_cvt_pk_bf16_f32 v108, v96, v97
	v_cvt_pk_bf16_f32 v109, v98, v99
	v_cvt_pk_bf16_f32 v110, v100, v101
	v_cvt_pk_bf16_f32 v111, v102, v103
	global_store_dwordx4 v122, v[104:107], s[74:75] sc1
	global_store_dwordx4 v122, v[108:111], s[74:75] offset:128 sc1
	s_nop 1
	s_mul_i32 s48, s81, 5
	s_add_u32 s48, s48, s39
	s_min_u32 s48, s48, s84
	s_sub_u32 s0, s48, 0x80
	s_cmpk_lt_u32 s0, 0x80
	s_cbranch_scc1 .Lptr_dec8_br
	s_cmpk_lt_u32 s0, 0x100
	s_cbranch_scc1 .Lptr_dec8_out
	s_cmpk_lt_u32 s0, 0x3c0
	s_cbranch_scc1 .Lptr_dec8_up
	s_sub_u32 s0, s0, 0x3c0
	s_lshr_b32 s2, s0, 4
	s_and_b32 s3, s0, 15
	s_lshl_b32 s12, s2, 19
	s_lshl_b32 s13, s3, 8
	s_add_u32 s12, s12, s13
	s_add_u32 s30, s21, s12
	s_addc_u32 s31, s68, 0
	s_mul_i32 s12, s3, 0x58000
	s_lshl_b32 s13, s2, 8
	s_add_u32 s12, s12, s13
	s_add_u32 s74, s6, s12
	s_addc_u32 s75, s7, 0
	s_movk_i32 s76, 0x1000
	s_movk_i32 s86, 0x1600
	s_branch .Lptr_dec8_done

.Lptr_dec8_done:
	v_mul_lo_u32 v123, v112, s76
	v_add_u32_e32 v118, v123, v113
	s_lshl_b32 vcc_lo, s76, 5
	v_add_u32_e32 v119, vcc_lo, v118
	v_add_u32_e32 v120, vcc_lo, v119
	v_add_u32_e32 v121, vcc_lo, v120
	global_load_dwordx4 v[56:59], v118, s[30:31] nt
	global_load_dwordx4 v[60:63], v119, s[30:31] nt
	global_load_dwordx4 v[64:67], v120, s[30:31] nt
	global_load_dwordx4 v[68:71], v121, s[30:31] nt
	s_waitcnt vmcnt(16)
	ds_write_b32 v114, v72 offset:0
	ds_write_b32 v114, v73 offset:4
	ds_write_b32 v114, v74 offset:8
	ds_write_b32 v114, v75 offset:12
	ds_write_b32 v114, v76 offset:8320
	ds_write_b32 v114, v77 offset:8324
	ds_write_b32 v114, v78 offset:8328
	ds_write_b32 v114, v79 offset:8332
	ds_write_b32 v114, v80 offset:16640
	ds_write_b32 v114, v81 offset:16644
	ds_write_b32 v114, v82 offset:16648
	ds_write_b32 v114, v83 offset:16652
	ds_write_b32 v114, v84 offset:24960
	ds_write_b32 v114, v85 offset:24964
	ds_write_b32 v114, v86 offset:24968
	ds_write_b32 v114, v87 offset:24972
	s_waitcnt lgkmcnt(0)
	s_barrier
	ds_read_b32 v88, v115 offset:0
	ds_read_b32 v89, v115 offset:260
	ds_read_b32 v90, v115 offset:520
	ds_read_b32 v91, v115 offset:780
	ds_read_b32 v92, v115 offset:1040
	ds_read_b32 v93, v115 offset:1300
	ds_read_b32 v94, v115 offset:1560
	ds_read_b32 v95, v115 offset:1820
	ds_read_b32 v96, v115 offset:16640
	ds_read_b32 v97, v115 offset:16900
	ds_read_b32 v98, v115 offset:17160
	ds_read_b32 v99, v115 offset:17420
	ds_read_b32 v100, v115 offset:17680
	ds_read_b32 v101, v115 offset:17940
	ds_read_b32 v102, v115 offset:18200
	ds_read_b32 v103, v115 offset:18460
	s_mul_i32 s48, s81, 2
	s_add_u32 s48, s48, s39
	s_min_u32 s48, s48, s84
	s_sub_u32 s0, s48, 0x80
	s_cmpk_lt_u32 s0, 0x80
	s_cbranch_scc1 .Lptr_dec9_br
	s_cmpk_lt_u32 s0, 0x100
	s_cbranch_scc1 .Lptr_dec9_out
	s_cmpk_lt_u32 s0, 0x3c0
	s_cbranch_scc1 .Lptr_dec9_up
	s_sub_u32 s0, s0, 0x3c0
	s_lshr_b32 s2, s0, 4
	s_and_b32 s3, s0, 15
	s_lshl_b32 s12, s2, 19
	s_lshl_b32 s13, s3, 8
	s_add_u32 s12, s12, s13
	s_add_u32 s30, s21, s12
	s_addc_u32 s31, s68, 0
	s_mul_i32 s12, s3, 0x58000
	s_lshl_b32 s13, s2, 8
	s_add_u32 s12, s12, s13
	s_add_u32 s74, s6, s12
	s_addc_u32 s75, s7, 0
	s_movk_i32 s76, 0x1000
	s_movk_i32 s86, 0x1600
	s_branch .Lptr_dec9_done

.Lptr_dec9_done:
	v_mul_lo_u32 v122, v116, s86
	v_add_u32_e32 v122, v122, v117
	s_waitcnt lgkmcnt(0)
	v_cvt_pk_bf16_f32 v104, v88, v89
	v_cvt_pk_bf16_f32 v105, v90, v91
	v_cvt_pk_bf16_f32 v106, v92, v93
	v_cvt_pk_bf16_f32 v107, v94, v95
	v_cvt_pk_bf16_f32 v108, v96, v97
	v_cvt_pk_bf16_f32 v109, v98, v99
	v_cvt_pk_bf16_f32 v110, v100, v101
	v_cvt_pk_bf16_f32 v111, v102, v103
	global_store_dwordx4 v122, v[104:107], s[74:75] sc1
	global_store_dwordx4 v122, v[108:111], s[74:75] offset:128 sc1
	s_nop 1
	s_mul_i32 s48, s81, 6
	s_add_u32 s48, s48, s39
	s_min_u32 s48, s48, s84
	s_sub_u32 s0, s48, 0x80
	s_cmpk_lt_u32 s0, 0x80
	s_cbranch_scc1 .Lptr_dec10_br
	s_cmpk_lt_u32 s0, 0x100
	s_cbranch_scc1 .Lptr_dec10_out
	s_cmpk_lt_u32 s0, 0x3c0
	s_cbranch_scc1 .Lptr_dec10_up
	s_sub_u32 s0, s0, 0x3c0
	s_lshr_b32 s2, s0, 4
	s_and_b32 s3, s0, 15
	s_lshl_b32 s12, s2, 19
	s_lshl_b32 s13, s3, 8
	s_add_u32 s12, s12, s13
	s_add_u32 s30, s21, s12
	s_addc_u32 s31, s68, 0
	s_mul_i32 s12, s3, 0x58000
	s_lshl_b32 s13, s2, 8
	s_add_u32 s12, s12, s13
	s_add_u32 s74, s6, s12
	s_addc_u32 s75, s7, 0
	s_movk_i32 s76, 0x1000
	s_movk_i32 s86, 0x1600
	s_branch .Lptr_dec10_done

.Lptr_dec10_done:
	v_mul_lo_u32 v123, v112, s76
	v_add_u32_e32 v118, v123, v113
	s_lshl_b32 vcc_lo, s76, 5
	v_add_u32_e32 v119, vcc_lo, v118
	v_add_u32_e32 v120, vcc_lo, v119
	v_add_u32_e32 v121, vcc_lo, v120
	global_load_dwordx4 v[72:75], v118, s[30:31] nt
	global_load_dwordx4 v[76:79], v119, s[30:31] nt
	global_load_dwordx4 v[80:83], v120, s[30:31] nt
	global_load_dwordx4 v[84:87], v121, s[30:31] nt
	s_waitcnt vmcnt(18)
	ds_write_b32 v114, v124 offset:33792
	ds_write_b32 v114, v125 offset:33796
	ds_write_b32 v114, v126 offset:33800
	ds_write_b32 v114, v127 offset:33804
	ds_write_b32 v114, v128 offset:42112
	ds_write_b32 v114, v129 offset:42116
	ds_write_b32 v114, v130 offset:42120
	ds_write_b32 v114, v131 offset:42124
	ds_write_b32 v114, v132 offset:50432
	ds_write_b32 v114, v133 offset:50436
	ds_write_b32 v114, v134 offset:50440
	ds_write_b32 v114, v135 offset:50444
	ds_write_b32 v114, v136 offset:58752
	ds_write_b32 v114, v137 offset:58756
	ds_write_b32 v114, v138 offset:58760
	ds_write_b32 v114, v139 offset:58764
	s_waitcnt lgkmcnt(0)
	s_barrier
	ds_read_b32 v88, v115 offset:33792
	ds_read_b32 v89, v115 offset:34052
	ds_read_b32 v90, v115 offset:34312
	ds_read_b32 v91, v115 offset:34572
	ds_read_b32 v92, v115 offset:34832
	ds_read_b32 v93, v115 offset:35092
	ds_read_b32 v94, v115 offset:35352
	ds_read_b32 v95, v115 offset:35612
	ds_read_b32 v96, v115 offset:50432
	ds_read_b32 v97, v115 offset:50692
	ds_read_b32 v98, v115 offset:50952
	ds_read_b32 v99, v115 offset:51212
	ds_read_b32 v100, v115 offset:51472
	ds_read_b32 v101, v115 offset:51732
	ds_read_b32 v102, v115 offset:51992
	ds_read_b32 v103, v115 offset:52252
	s_mul_i32 s48, s81, 3
	s_add_u32 s48, s48, s39
	s_min_u32 s48, s48, s84
	s_sub_u32 s0, s48, 0x80
	s_cmpk_lt_u32 s0, 0x80
	s_cbranch_scc1 .Lptr_dec11_br
	s_cmpk_lt_u32 s0, 0x100
	s_cbranch_scc1 .Lptr_dec11_out
	s_cmpk_lt_u32 s0, 0x3c0
	s_cbranch_scc1 .Lptr_dec11_up
	s_sub_u32 s0, s0, 0x3c0
	s_lshr_b32 s2, s0, 4
	s_and_b32 s3, s0, 15
	s_lshl_b32 s12, s2, 19
	s_lshl_b32 s13, s3, 8
	s_add_u32 s12, s12, s13
	s_add_u32 s30, s21, s12
	s_addc_u32 s31, s68, 0
	s_mul_i32 s12, s3, 0x58000
	s_lshl_b32 s13, s2, 8
	s_add_u32 s12, s12, s13
	s_add_u32 s74, s6, s12
	s_addc_u32 s75, s7, 0
	s_movk_i32 s76, 0x1000
	s_movk_i32 s86, 0x1600
	s_branch .Lptr_dec11_done

.Lptr_dec11_done:
	v_mul_lo_u32 v122, v116, s86
	v_add_u32_e32 v122, v122, v117
	s_waitcnt lgkmcnt(0)
	v_cvt_pk_bf16_f32 v104, v88, v89
	v_cvt_pk_bf16_f32 v105, v90, v91
	v_cvt_pk_bf16_f32 v106, v92, v93
	v_cvt_pk_bf16_f32 v107, v94, v95
	v_cvt_pk_bf16_f32 v108, v96, v97
	v_cvt_pk_bf16_f32 v109, v98, v99
	v_cvt_pk_bf16_f32 v110, v100, v101
	v_cvt_pk_bf16_f32 v111, v102, v103
	global_store_dwordx4 v122, v[104:107], s[74:75] sc1
	global_store_dwordx4 v122, v[108:111], s[74:75] offset:128 sc1
	s_nop 1
	s_waitcnt vmcnt(14)
	ds_write_b32 v114, v40 offset:0
	ds_write_b32 v114, v41 offset:4
	ds_write_b32 v114, v42 offset:8
	ds_write_b32 v114, v43 offset:12
	ds_write_b32 v114, v44 offset:8320
	ds_write_b32 v114, v45 offset:8324
	ds_write_b32 v114, v46 offset:8328
	ds_write_b32 v114, v47 offset:8332
	ds_write_b32 v114, v48 offset:16640
	ds_write_b32 v114, v49 offset:16644
	ds_write_b32 v114, v50 offset:16648
	ds_write_b32 v114, v51 offset:16652
	ds_write_b32 v114, v52 offset:24960
	ds_write_b32 v114, v53 offset:24964
	ds_write_b32 v114, v54 offset:24968
	ds_write_b32 v114, v55 offset:24972
	s_waitcnt lgkmcnt(0)
	s_barrier
	ds_read_b32 v88, v115 offset:0
	ds_read_b32 v89, v115 offset:260
	ds_read_b32 v90, v115 offset:520
	ds_read_b32 v91, v115 offset:780
	ds_read_b32 v92, v115 offset:1040
	ds_read_b32 v93, v115 offset:1300
	ds_read_b32 v94, v115 offset:1560
	ds_read_b32 v95, v115 offset:1820
	ds_read_b32 v96, v115 offset:16640
	ds_read_b32 v97, v115 offset:16900
	ds_read_b32 v98, v115 offset:17160
	ds_read_b32 v99, v115 offset:17420
	ds_read_b32 v100, v115 offset:17680
	ds_read_b32 v101, v115 offset:17940
	ds_read_b32 v102, v115 offset:18200
	ds_read_b32 v103, v115 offset:18460
	s_mul_i32 s48, s81, 4
	s_add_u32 s48, s48, s39
	s_min_u32 s48, s48, s84
	s_sub_u32 s0, s48, 0x80
	s_cmpk_lt_u32 s0, 0x80
	s_cbranch_scc1 .Lptr_dec12_br
	s_cmpk_lt_u32 s0, 0x100
	s_cbranch_scc1 .Lptr_dec12_out
	s_cmpk_lt_u32 s0, 0x3c0
	s_cbranch_scc1 .Lptr_dec12_up
	s_sub_u32 s0, s0, 0x3c0
	s_lshr_b32 s2, s0, 4
	s_and_b32 s3, s0, 15
	s_lshl_b32 s12, s2, 19
	s_lshl_b32 s13, s3, 8
	s_add_u32 s12, s12, s13
	s_add_u32 s30, s21, s12
	s_addc_u32 s31, s68, 0
	s_mul_i32 s12, s3, 0x58000
	s_lshl_b32 s13, s2, 8
	s_add_u32 s12, s12, s13
	s_add_u32 s74, s6, s12
	s_addc_u32 s75, s7, 0
	s_movk_i32 s76, 0x1000
	s_movk_i32 s86, 0x1600
	s_branch .Lptr_dec12_done

.Lptr_dec12_done:
	v_mul_lo_u32 v122, v116, s86
	v_add_u32_e32 v122, v122, v117
	s_waitcnt lgkmcnt(0)
	v_cvt_pk_bf16_f32 v104, v88, v89
	v_cvt_pk_bf16_f32 v105, v90, v91
	v_cvt_pk_bf16_f32 v106, v92, v93
	v_cvt_pk_bf16_f32 v107, v94, v95
	v_cvt_pk_bf16_f32 v108, v96, v97
	v_cvt_pk_bf16_f32 v109, v98, v99
	v_cvt_pk_bf16_f32 v110, v100, v101
	v_cvt_pk_bf16_f32 v111, v102, v103
	global_store_dwordx4 v122, v[104:107], s[74:75] sc1
	global_store_dwordx4 v122, v[108:111], s[74:75] offset:128 sc1
	s_nop 1
	s_waitcnt vmcnt(10)
	ds_write_b32 v114, v56 offset:33792
	ds_write_b32 v114, v57 offset:33796
	ds_write_b32 v114, v58 offset:33800
	ds_write_b32 v114, v59 offset:33804
	ds_write_b32 v114, v60 offset:42112
	ds_write_b32 v114, v61 offset:42116
	ds_write_b32 v114, v62 offset:42120
	ds_write_b32 v114, v63 offset:42124
	ds_write_b32 v114, v64 offset:50432
	ds_write_b32 v114, v65 offset:50436
	ds_write_b32 v114, v66 offset:50440
	ds_write_b32 v114, v67 offset:50444
	ds_write_b32 v114, v68 offset:58752
	ds_write_b32 v114, v69 offset:58756
	ds_write_b32 v114, v70 offset:58760
	ds_write_b32 v114, v71 offset:58764
	s_waitcnt lgkmcnt(0)
	s_barrier
	ds_read_b32 v88, v115 offset:33792
	ds_read_b32 v89, v115 offset:34052
	ds_read_b32 v90, v115 offset:34312
	ds_read_b32 v91, v115 offset:34572
	ds_read_b32 v92, v115 offset:34832
	ds_read_b32 v93, v115 offset:35092
	ds_read_b32 v94, v115 offset:35352
	ds_read_b32 v95, v115 offset:35612
	ds_read_b32 v96, v115 offset:50432
	ds_read_b32 v97, v115 offset:50692
	ds_read_b32 v98, v115 offset:50952
	ds_read_b32 v99, v115 offset:51212
	ds_read_b32 v100, v115 offset:51472
	ds_read_b32 v101, v115 offset:51732
	ds_read_b32 v102, v115 offset:51992
	ds_read_b32 v103, v115 offset:52252
	s_mul_i32 s48, s81, 5
	s_add_u32 s48, s48, s39
	s_min_u32 s48, s48, s84
	s_sub_u32 s0, s48, 0x80
	s_cmpk_lt_u32 s0, 0x80
	s_cbranch_scc1 .Lptr_dec13_br
	s_cmpk_lt_u32 s0, 0x100
	s_cbranch_scc1 .Lptr_dec13_out
	s_cmpk_lt_u32 s0, 0x3c0
	s_cbranch_scc1 .Lptr_dec13_up
	s_sub_u32 s0, s0, 0x3c0
	s_lshr_b32 s2, s0, 4
	s_and_b32 s3, s0, 15
	s_lshl_b32 s12, s2, 19
	s_lshl_b32 s13, s3, 8
	s_add_u32 s12, s12, s13
	s_add_u32 s30, s21, s12
	s_addc_u32 s31, s68, 0
	s_mul_i32 s12, s3, 0x58000
	s_lshl_b32 s13, s2, 8
	s_add_u32 s12, s12, s13
	s_add_u32 s74, s6, s12
	s_addc_u32 s75, s7, 0
	s_movk_i32 s76, 0x1000
	s_movk_i32 s86, 0x1600
	s_branch .Lptr_dec13_done

.Lptr_dec13_done:
	v_mul_lo_u32 v122, v116, s86
	v_add_u32_e32 v122, v122, v117
	s_waitcnt lgkmcnt(0)
	v_cvt_pk_bf16_f32 v104, v88, v89
	v_cvt_pk_bf16_f32 v105, v90, v91
	v_cvt_pk_bf16_f32 v106, v92, v93
	v_cvt_pk_bf16_f32 v107, v94, v95
	v_cvt_pk_bf16_f32 v108, v96, v97
	v_cvt_pk_bf16_f32 v109, v98, v99
	v_cvt_pk_bf16_f32 v110, v100, v101
	v_cvt_pk_bf16_f32 v111, v102, v103
	global_store_dwordx4 v122, v[104:107], s[74:75] sc1
	global_store_dwordx4 v122, v[108:111], s[74:75] offset:128 sc1
	s_nop 1
	s_waitcnt vmcnt(6)
	ds_write_b32 v114, v72 offset:0
	ds_write_b32 v114, v73 offset:4
	ds_write_b32 v114, v74 offset:8
	ds_write_b32 v114, v75 offset:12
	ds_write_b32 v114, v76 offset:8320
	ds_write_b32 v114, v77 offset:8324
	ds_write_b32 v114, v78 offset:8328
	ds_write_b32 v114, v79 offset:8332
	ds_write_b32 v114, v80 offset:16640
	ds_write_b32 v114, v81 offset:16644
	ds_write_b32 v114, v82 offset:16648
	ds_write_b32 v114, v83 offset:16652
	ds_write_b32 v114, v84 offset:24960
	ds_write_b32 v114, v85 offset:24964
	ds_write_b32 v114, v86 offset:24968
	ds_write_b32 v114, v87 offset:24972
	s_waitcnt lgkmcnt(0)
	s_barrier
	ds_read_b32 v88, v115 offset:0
	ds_read_b32 v89, v115 offset:260
	ds_read_b32 v90, v115 offset:520
	ds_read_b32 v91, v115 offset:780
	ds_read_b32 v92, v115 offset:1040
	ds_read_b32 v93, v115 offset:1300
	ds_read_b32 v94, v115 offset:1560
	ds_read_b32 v95, v115 offset:1820
	ds_read_b32 v96, v115 offset:16640
	ds_read_b32 v97, v115 offset:16900
	ds_read_b32 v98, v115 offset:17160
	ds_read_b32 v99, v115 offset:17420
	ds_read_b32 v100, v115 offset:17680
	ds_read_b32 v101, v115 offset:17940
	ds_read_b32 v102, v115 offset:18200
	ds_read_b32 v103, v115 offset:18460
	s_mul_i32 s48, s81, 6
	s_add_u32 s48, s48, s39
	s_min_u32 s48, s48, s84
	s_sub_u32 s0, s48, 0x80
	s_cmpk_lt_u32 s0, 0x80
	s_cbranch_scc1 .Lptr_dec14_br
	s_cmpk_lt_u32 s0, 0x100
	s_cbranch_scc1 .Lptr_dec14_out
	s_cmpk_lt_u32 s0, 0x3c0
	s_cbranch_scc1 .Lptr_dec14_up
	s_sub_u32 s0, s0, 0x3c0
	s_lshr_b32 s2, s0, 4
	s_and_b32 s3, s0, 15
	s_lshl_b32 s12, s2, 19
	s_lshl_b32 s13, s3, 8
	s_add_u32 s12, s12, s13
	s_add_u32 s30, s21, s12
	s_addc_u32 s31, s68, 0
	s_mul_i32 s12, s3, 0x58000
	s_lshl_b32 s13, s2, 8
	s_add_u32 s12, s12, s13
	s_add_u32 s74, s6, s12
	s_addc_u32 s75, s7, 0
	s_movk_i32 s76, 0x1000
	s_movk_i32 s86, 0x1600
	s_branch .Lptr_dec14_done

.Lptr_dec14_done:
	v_mul_lo_u32 v122, v116, s86
	v_add_u32_e32 v122, v122, v117
	s_waitcnt lgkmcnt(0)
	v_cvt_pk_bf16_f32 v104, v88, v89
	v_cvt_pk_bf16_f32 v105, v90, v91
	v_cvt_pk_bf16_f32 v106, v92, v93
	v_cvt_pk_bf16_f32 v107, v94, v95
	v_cvt_pk_bf16_f32 v108, v96, v97
	v_cvt_pk_bf16_f32 v109, v98, v99
	v_cvt_pk_bf16_f32 v110, v100, v101
	v_cvt_pk_bf16_f32 v111, v102, v103
	global_store_dwordx4 v122, v[104:107], s[74:75] sc1
	global_store_dwordx4 v122, v[108:111], s[74:75] offset:128 sc1
	s_nop 1
	s_waitcnt vmcnt(0)
	s_barrier
	s_branch .LBB0_602

.Ln1t_kdone:
	v_lshrrev_b32_e32 v112, 4, v1
	v_and_b32_e32 v113, 15, v1
	v_lshlrev_b32_e32 v113, 4, v113
	v_mul_u32_u24_e32 v114, 0x104, v112
	v_add_u32_e32 v114, v114, v113
	v_lshrrev_b32_e32 v116, 3, v1
	v_and_b32_e32 v117, 7, v1
	v_mul_u32_u24_e32 v115, 0x820, v117
	v_lshl_add_u32 v115, v116, 2, v115
	v_lshlrev_b32_e32 v117, 4, v117
	s_mul_i32 s48, s73, 0
	s_add_u32 s48, s48, s74
	s_min_u32 s48, s48, s72
	s_mov_b32 s0, s48
	s_mul_i32 s2, s0, 0x4ed
	s_lshr_b32 s2, s2, 17
	s_mul_i32 s3, s2, 0x68
	s_sub_u32 s3, s0, s3
	s_mul_i32 s14, s2, 0x340000
	s_lshl_b32 s0, s3, 8
	s_add_u32 s14, s14, s0
	s_add_u32 s6, s68, s14
	s_addc_u32 s7, s69, 0
	s_lshl_b32 s14, s3, 17
	s_lshl_b32 s0, s2, 8
	s_add_u32 s14, s14, s0
	s_add_u32 s8, s70, s14
	s_addc_u32 s9, s71, 0
	s_movk_i32 s12, 0x6800
	s_movk_i32 s13, 0x800
	v_mul_lo_u32 v123, v112, s12
	v_add_u32_e32 v118, v123, v113
	s_lshl_b32 vcc_lo, s12, 5
	v_add_u32_e32 v119, vcc_lo, v118
	v_add_u32_e32 v120, vcc_lo, v119
	v_add_u32_e32 v121, vcc_lo, v120
	global_load_dwordx4 v[40:43], v118, s[6:7] nt
	global_load_dwordx4 v[44:47], v119, s[6:7] nt
	global_load_dwordx4 v[48:51], v120, s[6:7] nt
	global_load_dwordx4 v[52:55], v121, s[6:7] nt
	s_mul_i32 s48, s73, 1
	s_add_u32 s48, s48, s74
	s_min_u32 s48, s48, s72
	s_mov_b32 s0, s48
	s_mul_i32 s2, s0, 0x4ed
	s_lshr_b32 s2, s2, 17
	s_mul_i32 s3, s2, 0x68
	s_sub_u32 s3, s0, s3
	s_mul_i32 s14, s2, 0x340000
	s_lshl_b32 s0, s3, 8
	s_add_u32 s14, s14, s0
	s_add_u32 s6, s68, s14
	s_addc_u32 s7, s69, 0
	s_lshl_b32 s14, s3, 17
	s_lshl_b32 s0, s2, 8
	s_add_u32 s14, s14, s0
	s_add_u32 s8, s70, s14
	s_addc_u32 s9, s71, 0
	s_movk_i32 s12, 0x6800
	s_movk_i32 s13, 0x800
	v_mul_lo_u32 v123, v112, s12
	v_add_u32_e32 v118, v123, v113
	s_lshl_b32 vcc_lo, s12, 5
	v_add_u32_e32 v119, vcc_lo, v118
	v_add_u32_e32 v120, vcc_lo, v119
	v_add_u32_e32 v121, vcc_lo, v120
	global_load_dwordx4 v[56:59], v118, s[6:7] nt
	global_load_dwordx4 v[60:63], v119, s[6:7] nt
	global_load_dwordx4 v[64:67], v120, s[6:7] nt
	global_load_dwordx4 v[68:71], v121, s[6:7] nt
	s_waitcnt vmcnt(4)
	ds_write_b32 v114, v40 offset:0
	ds_write_b32 v114, v41 offset:4
	ds_write_b32 v114, v42 offset:8
	ds_write_b32 v114, v43 offset:12
	ds_write_b32 v114, v44 offset:8320
	ds_write_b32 v114, v45 offset:8324
	ds_write_b32 v114, v46 offset:8328
	ds_write_b32 v114, v47 offset:8332
	ds_write_b32 v114, v48 offset:16640
	ds_write_b32 v114, v49 offset:16644
	ds_write_b32 v114, v50 offset:16648
	ds_write_b32 v114, v51 offset:16652
	ds_write_b32 v114, v52 offset:24960
	ds_write_b32 v114, v53 offset:24964
	ds_write_b32 v114, v54 offset:24968
	ds_write_b32 v114, v55 offset:24972
	s_waitcnt lgkmcnt(0)
	s_barrier
	ds_read_b32 v88, v115 offset:0
	ds_read_b32 v89, v115 offset:260
	ds_read_b32 v90, v115 offset:520
	ds_read_b32 v91, v115 offset:780
	ds_read_b32 v92, v115 offset:1040
	ds_read_b32 v93, v115 offset:1300
	ds_read_b32 v94, v115 offset:1560
	ds_read_b32 v95, v115 offset:1820
	ds_read_b32 v96, v115 offset:16640
	ds_read_b32 v97, v115 offset:16900
	ds_read_b32 v98, v115 offset:17160
	ds_read_b32 v99, v115 offset:17420
	ds_read_b32 v100, v115 offset:17680
	ds_read_b32 v101, v115 offset:17940
	ds_read_b32 v102, v115 offset:18200
	ds_read_b32 v103, v115 offset:18460
	s_mul_i32 s48, s73, 0
	s_add_u32 s48, s48, s74
	s_min_u32 s48, s48, s72
	s_mov_b32 s0, s48
	s_mul_i32 s2, s0, 0x4ed
	s_lshr_b32 s2, s2, 17
	s_mul_i32 s3, s2, 0x68
	s_sub_u32 s3, s0, s3
	s_mul_i32 s14, s2, 0x340000
	s_lshl_b32 s0, s3, 8
	s_add_u32 s14, s14, s0
	s_add_u32 s6, s68, s14
	s_addc_u32 s7, s69, 0
	s_lshl_b32 s14, s3, 17
	s_lshl_b32 s0, s2, 8
	s_add_u32 s14, s14, s0
	s_add_u32 s8, s70, s14
	s_addc_u32 s9, s71, 0
	s_movk_i32 s12, 0x6800
	s_movk_i32 s13, 0x800
	v_mul_lo_u32 v122, v116, s13
	v_add_u32_e32 v122, v122, v117
	s_waitcnt lgkmcnt(0)
	v_cvt_pk_bf16_f32 v104, v88, v89
	v_cvt_pk_bf16_f32 v105, v90, v91
	v_cvt_pk_bf16_f32 v106, v92, v93
	v_cvt_pk_bf16_f32 v107, v94, v95
	v_cvt_pk_bf16_f32 v108, v96, v97
	v_cvt_pk_bf16_f32 v109, v98, v99
	v_cvt_pk_bf16_f32 v110, v100, v101
	v_cvt_pk_bf16_f32 v111, v102, v103
	global_store_dwordx4 v122, v[104:107], s[8:9] sc1
	global_store_dwordx4 v122, v[108:111], s[8:9] offset:128 sc1
	s_nop 1
	s_waitcnt vmcnt(2)
	ds_write_b32 v114, v56 offset:33792
	ds_write_b32 v114, v57 offset:33796
	ds_write_b32 v114, v58 offset:33800
	ds_write_b32 v114, v59 offset:33804
	ds_write_b32 v114, v60 offset:42112
	ds_write_b32 v114, v61 offset:42116
	ds_write_b32 v114, v62 offset:42120
	ds_write_b32 v114, v63 offset:42124
	ds_write_b32 v114, v64 offset:50432
	ds_write_b32 v114, v65 offset:50436
	ds_write_b32 v114, v66 offset:50440
	ds_write_b32 v114, v67 offset:50444
	ds_write_b32 v114, v68 offset:58752
	ds_write_b32 v114, v69 offset:58756
	ds_write_b32 v114, v70 offset:58760
	ds_write_b32 v114, v71 offset:58764
	s_waitcnt lgkmcnt(0)
	s_barrier
	ds_read_b32 v88, v115 offset:33792
	ds_read_b32 v89, v115 offset:34052
	ds_read_b32 v90, v115 offset:34312
	ds_read_b32 v91, v115 offset:34572
	ds_read_b32 v92, v115 offset:34832
	ds_read_b32 v93, v115 offset:35092
	ds_read_b32 v94, v115 offset:35352
	ds_read_b32 v95, v115 offset:35612
	ds_read_b32 v96, v115 offset:50432
	ds_read_b32 v97, v115 offset:50692
	ds_read_b32 v98, v115 offset:50952
	ds_read_b32 v99, v115 offset:51212
	ds_read_b32 v100, v115 offset:51472
	ds_read_b32 v101, v115 offset:51732
	ds_read_b32 v102, v115 offset:51992
	ds_read_b32 v103, v115 offset:52252
	s_mul_i32 s48, s73, 1
	s_add_u32 s48, s48, s74
	s_min_u32 s48, s48, s72
	s_mov_b32 s0, s48
	s_mul_i32 s2, s0, 0x4ed
	s_lshr_b32 s2, s2, 17
	s_mul_i32 s3, s2, 0x68
	s_sub_u32 s3, s0, s3
	s_mul_i32 s14, s2, 0x340000
	s_lshl_b32 s0, s3, 8
	s_add_u32 s14, s14, s0
	s_add_u32 s6, s68, s14
	s_addc_u32 s7, s69, 0
	s_lshl_b32 s14, s3, 17
	s_lshl_b32 s0, s2, 8
	s_add_u32 s14, s14, s0
	s_add_u32 s8, s70, s14
	s_addc_u32 s9, s71, 0
	s_movk_i32 s12, 0x6800
	s_movk_i32 s13, 0x800
	v_mul_lo_u32 v122, v116, s13
	v_add_u32_e32 v122, v122, v117
	s_waitcnt lgkmcnt(0)
	v_cvt_pk_bf16_f32 v104, v88, v89
	v_cvt_pk_bf16_f32 v105, v90, v91
	v_cvt_pk_bf16_f32 v106, v92, v93
	v_cvt_pk_bf16_f32 v107, v94, v95
	v_cvt_pk_bf16_f32 v108, v96, v97
	v_cvt_pk_bf16_f32 v109, v98, v99
	v_cvt_pk_bf16_f32 v110, v100, v101
	v_cvt_pk_bf16_f32 v111, v102, v103
	global_store_dwordx4 v122, v[104:107], s[8:9] sc1
	global_store_dwordx4 v122, v[108:111], s[8:9] offset:128 sc1
	s_nop 1
	s_waitcnt vmcnt(0)
	s_barrier
	s_branch .LBB0_692

.Lp0t_kdone:
	v_lshrrev_b32_e32 v112, 4, v1
	v_and_b32_e32 v113, 15, v1
	v_lshlrev_b32_e32 v113, 4, v113
	v_mul_u32_u24_e32 v114, 0x104, v112
	v_add_u32_e32 v114, v114, v113
	v_lshrrev_b32_e32 v116, 3, v1
	v_and_b32_e32 v117, 7, v1
	v_mul_u32_u24_e32 v115, 0x820, v117
	v_lshl_add_u32 v115, v116, 2, v115
	v_lshlrev_b32_e32 v117, 4, v117
	s_mul_i32 s48, s85, 0
	s_add_u32 s48, s48, s86
	s_min_u32 s48, s48, s84
	s_sub_u32 s0, s48, 0xe0
	s_mul_i32 s2, s0, 0x4ed
	s_lshr_b32 s2, s2, 17
	s_mul_i32 s3, s2, 0x68
	s_sub_u32 s3, s0, s3
	s_mul_i32 s4, s2, 0x340000
	s_lshl_b32 s0, s3, 8
	s_add_u32 s4, s4, s0
	s_add_u32 s6, s80, s4
	s_addc_u32 s7, s81, 0
	s_lshl_b32 s4, s3, 17
	s_lshl_b32 s0, s2, 8
	s_add_u32 s4, s4, s0
	s_add_u32 s8, s82, s4
	s_addc_u32 s9, s83, 0
	s_movk_i32 s10, 0x6800
	s_movk_i32 s11, 0x800
	v_mul_lo_u32 v123, v112, s10
	v_add_u32_e32 v118, v123, v113
	s_lshl_b32 vcc_lo, s10, 5
	v_add_u32_e32 v119, vcc_lo, v118
	v_add_u32_e32 v120, vcc_lo, v119
	v_add_u32_e32 v121, vcc_lo, v120
	global_load_dwordx4 v[40:43], v118, s[6:7] nt
	global_load_dwordx4 v[44:47], v119, s[6:7] nt
	global_load_dwordx4 v[48:51], v120, s[6:7] nt
	global_load_dwordx4 v[52:55], v121, s[6:7] nt
	s_mul_i32 s48, s85, 1
	s_add_u32 s48, s48, s86
	s_min_u32 s48, s48, s84
	s_sub_u32 s0, s48, 0xe0
	s_mul_i32 s2, s0, 0x4ed
	s_lshr_b32 s2, s2, 17
	s_mul_i32 s3, s2, 0x68
	s_sub_u32 s3, s0, s3
	s_mul_i32 s4, s2, 0x340000
	s_lshl_b32 s0, s3, 8
	s_add_u32 s4, s4, s0
	s_add_u32 s6, s80, s4
	s_addc_u32 s7, s81, 0
	s_lshl_b32 s4, s3, 17
	s_lshl_b32 s0, s2, 8
	s_add_u32 s4, s4, s0
	s_add_u32 s8, s82, s4
	s_addc_u32 s9, s83, 0
	s_movk_i32 s10, 0x6800
	s_movk_i32 s11, 0x800
	v_mul_lo_u32 v123, v112, s10
	v_add_u32_e32 v118, v123, v113
	s_lshl_b32 vcc_lo, s10, 5
	v_add_u32_e32 v119, vcc_lo, v118
	v_add_u32_e32 v120, vcc_lo, v119
	v_add_u32_e32 v121, vcc_lo, v120
	global_load_dwordx4 v[56:59], v118, s[6:7] nt
	global_load_dwordx4 v[60:63], v119, s[6:7] nt
	global_load_dwordx4 v[64:67], v120, s[6:7] nt
	global_load_dwordx4 v[68:71], v121, s[6:7] nt
	s_mul_i32 s48, s85, 2
	s_add_u32 s48, s48, s86
	s_min_u32 s48, s48, s84
	s_sub_u32 s0, s48, 0xe0
	s_mul_i32 s2, s0, 0x4ed
	s_lshr_b32 s2, s2, 17
	s_mul_i32 s3, s2, 0x68
	s_sub_u32 s3, s0, s3
	s_mul_i32 s4, s2, 0x340000
	s_lshl_b32 s0, s3, 8
	s_add_u32 s4, s4, s0
	s_add_u32 s6, s80, s4
	s_addc_u32 s7, s81, 0
	s_lshl_b32 s4, s3, 17
	s_lshl_b32 s0, s2, 8
	s_add_u32 s4, s4, s0
	s_add_u32 s8, s82, s4
	s_addc_u32 s9, s83, 0
	s_movk_i32 s10, 0x6800
	s_movk_i32 s11, 0x800
	v_mul_lo_u32 v123, v112, s10
	v_add_u32_e32 v118, v123, v113
	s_lshl_b32 vcc_lo, s10, 5
	v_add_u32_e32 v119, vcc_lo, v118
	v_add_u32_e32 v120, vcc_lo, v119
	v_add_u32_e32 v121, vcc_lo, v120
	global_load_dwordx4 v[72:75], v118, s[6:7] nt
	global_load_dwordx4 v[76:79], v119, s[6:7] nt
	global_load_dwordx4 v[80:83], v120, s[6:7] nt
	global_load_dwordx4 v[84:87], v121, s[6:7] nt
	s_mul_i32 s48, s85, 3
	s_add_u32 s48, s48, s86
	s_min_u32 s48, s48, s84
	s_sub_u32 s0, s48, 0xe0
	s_mul_i32 s2, s0, 0x4ed
	s_lshr_b32 s2, s2, 17
	s_mul_i32 s3, s2, 0x68
	s_sub_u32 s3, s0, s3
	s_mul_i32 s4, s2, 0x340000
	s_lshl_b32 s0, s3, 8
	s_add_u32 s4, s4, s0
	s_add_u32 s6, s80, s4
	s_addc_u32 s7, s81, 0
	s_lshl_b32 s4, s3, 17
	s_lshl_b32 s0, s2, 8
	s_add_u32 s4, s4, s0
	s_add_u32 s8, s82, s4
	s_addc_u32 s9, s83, 0
	s_movk_i32 s10, 0x6800
	s_movk_i32 s11, 0x800
	v_mul_lo_u32 v123, v112, s10
	v_add_u32_e32 v118, v123, v113
	s_lshl_b32 vcc_lo, s10, 5
	v_add_u32_e32 v119, vcc_lo, v118
	v_add_u32_e32 v120, vcc_lo, v119
	v_add_u32_e32 v121, vcc_lo, v120
	global_load_dwordx4 v[124:127], v118, s[6:7] nt
	global_load_dwordx4 v[128:131], v119, s[6:7] nt
	global_load_dwordx4 v[132:135], v120, s[6:7] nt
	global_load_dwordx4 v[136:139], v121, s[6:7] nt
	s_waitcnt vmcnt(12)
	ds_write_b32 v114, v40 offset:0
	ds_write_b32 v114, v41 offset:4
	ds_write_b32 v114, v42 offset:8
	ds_write_b32 v114, v43 offset:12
	ds_write_b32 v114, v44 offset:8320
	ds_write_b32 v114, v45 offset:8324
	ds_write_b32 v114, v46 offset:8328
	ds_write_b32 v114, v47 offset:8332
	ds_write_b32 v114, v48 offset:16640
	ds_write_b32 v114, v49 offset:16644
	ds_write_b32 v114, v50 offset:16648
	ds_write_b32 v114, v51 offset:16652
	ds_write_b32 v114, v52 offset:24960
	ds_write_b32 v114, v53 offset:24964
	ds_write_b32 v114, v54 offset:24968
	ds_write_b32 v114, v55 offset:24972
	s_waitcnt lgkmcnt(0)
	s_barrier
	ds_read_b32 v88, v115 offset:0
	ds_read_b32 v89, v115 offset:260
	ds_read_b32 v90, v115 offset:520
	ds_read_b32 v91, v115 offset:780
	ds_read_b32 v92, v115 offset:1040
	ds_read_b32 v93, v115 offset:1300
	ds_read_b32 v94, v115 offset:1560
	ds_read_b32 v95, v115 offset:1820
	ds_read_b32 v96, v115 offset:16640
	ds_read_b32 v97, v115 offset:16900
	ds_read_b32 v98, v115 offset:17160
	ds_read_b32 v99, v115 offset:17420
	ds_read_b32 v100, v115 offset:17680
	ds_read_b32 v101, v115 offset:17940
	ds_read_b32 v102, v115 offset:18200
	ds_read_b32 v103, v115 offset:18460
	s_mul_i32 s48, s85, 0
	s_add_u32 s48, s48, s86
	s_min_u32 s48, s48, s84
	s_sub_u32 s0, s48, 0xe0
	s_mul_i32 s2, s0, 0x4ed
	s_lshr_b32 s2, s2, 17
	s_mul_i32 s3, s2, 0x68
	s_sub_u32 s3, s0, s3
	s_mul_i32 s4, s2, 0x340000
	s_lshl_b32 s0, s3, 8
	s_add_u32 s4, s4, s0
	s_add_u32 s6, s80, s4
	s_addc_u32 s7, s81, 0
	s_lshl_b32 s4, s3, 17
	s_lshl_b32 s0, s2, 8
	s_add_u32 s4, s4, s0
	s_add_u32 s8, s82, s4
	s_addc_u32 s9, s83, 0
	s_movk_i32 s10, 0x6800
	s_movk_i32 s11, 0x800
	v_mul_lo_u32 v122, v116, s11
	v_add_u32_e32 v122, v122, v117
	s_waitcnt lgkmcnt(0)
	v_cvt_pk_bf16_f32 v104, v88, v89
	v_cvt_pk_bf16_f32 v105, v90, v91
	v_cvt_pk_bf16_f32 v106, v92, v93
	v_cvt_pk_bf16_f32 v107, v94, v95
	v_cvt_pk_bf16_f32 v108, v96, v97
	v_cvt_pk_bf16_f32 v109, v98, v99
	v_cvt_pk_bf16_f32 v110, v100, v101
	v_cvt_pk_bf16_f32 v111, v102, v103
	global_store_dwordx4 v122, v[104:107], s[8:9] sc1
	global_store_dwordx4 v122, v[108:111], s[8:9] offset:128 sc1
	s_nop 1
	s_waitcnt vmcnt(10)
	ds_write_b32 v114, v56 offset:33792
	ds_write_b32 v114, v57 offset:33796
	ds_write_b32 v114, v58 offset:33800
	ds_write_b32 v114, v59 offset:33804
	ds_write_b32 v114, v60 offset:42112
	ds_write_b32 v114, v61 offset:42116
	ds_write_b32 v114, v62 offset:42120
	ds_write_b32 v114, v63 offset:42124
	ds_write_b32 v114, v64 offset:50432
	ds_write_b32 v114, v65 offset:50436
	ds_write_b32 v114, v66 offset:50440
	ds_write_b32 v114, v67 offset:50444
	ds_write_b32 v114, v68 offset:58752
	ds_write_b32 v114, v69 offset:58756
	ds_write_b32 v114, v70 offset:58760
	ds_write_b32 v114, v71 offset:58764
	s_waitcnt lgkmcnt(0)
	s_barrier
	ds_read_b32 v88, v115 offset:33792
	ds_read_b32 v89, v115 offset:34052
	ds_read_b32 v90, v115 offset:34312
	ds_read_b32 v91, v115 offset:34572
	ds_read_b32 v92, v115 offset:34832
	ds_read_b32 v93, v115 offset:35092
	ds_read_b32 v94, v115 offset:35352
	ds_read_b32 v95, v115 offset:35612
	ds_read_b32 v96, v115 offset:50432
	ds_read_b32 v97, v115 offset:50692
	ds_read_b32 v98, v115 offset:50952
	ds_read_b32 v99, v115 offset:51212
	ds_read_b32 v100, v115 offset:51472
	ds_read_b32 v101, v115 offset:51732
	ds_read_b32 v102, v115 offset:51992
	ds_read_b32 v103, v115 offset:52252
	s_mul_i32 s48, s85, 1
	s_add_u32 s48, s48, s86
	s_min_u32 s48, s48, s84
	s_sub_u32 s0, s48, 0xe0
	s_mul_i32 s2, s0, 0x4ed
	s_lshr_b32 s2, s2, 17
	s_mul_i32 s3, s2, 0x68
	s_sub_u32 s3, s0, s3
	s_mul_i32 s4, s2, 0x340000
	s_lshl_b32 s0, s3, 8
	s_add_u32 s4, s4, s0
	s_add_u32 s6, s80, s4
	s_addc_u32 s7, s81, 0
	s_lshl_b32 s4, s3, 17
	s_lshl_b32 s0, s2, 8
	s_add_u32 s4, s4, s0
	s_add_u32 s8, s82, s4
	s_addc_u32 s9, s83, 0
	s_movk_i32 s10, 0x6800
	s_movk_i32 s11, 0x800
	v_mul_lo_u32 v122, v116, s11
	v_add_u32_e32 v122, v122, v117
	s_waitcnt lgkmcnt(0)
	v_cvt_pk_bf16_f32 v104, v88, v89
	v_cvt_pk_bf16_f32 v105, v90, v91
	v_cvt_pk_bf16_f32 v106, v92, v93
	v_cvt_pk_bf16_f32 v107, v94, v95
	v_cvt_pk_bf16_f32 v108, v96, v97
	v_cvt_pk_bf16_f32 v109, v98, v99
	v_cvt_pk_bf16_f32 v110, v100, v101
	v_cvt_pk_bf16_f32 v111, v102, v103
	global_store_dwordx4 v122, v[104:107], s[8:9] sc1
	global_store_dwordx4 v122, v[108:111], s[8:9] offset:128 sc1
	s_nop 1
	s_waitcnt vmcnt(8)
	ds_write_b32 v114, v72 offset:0
	ds_write_b32 v114, v73 offset:4
	ds_write_b32 v114, v74 offset:8
	ds_write_b32 v114, v75 offset:12
	ds_write_b32 v114, v76 offset:8320
	ds_write_b32 v114, v77 offset:8324
	ds_write_b32 v114, v78 offset:8328
	ds_write_b32 v114, v79 offset:8332
	ds_write_b32 v114, v80 offset:16640
	ds_write_b32 v114, v81 offset:16644
	ds_write_b32 v114, v82 offset:16648
	ds_write_b32 v114, v83 offset:16652
	ds_write_b32 v114, v84 offset:24960
	ds_write_b32 v114, v85 offset:24964
	ds_write_b32 v114, v86 offset:24968
	ds_write_b32 v114, v87 offset:24972
	s_waitcnt lgkmcnt(0)
	s_barrier
	ds_read_b32 v88, v115 offset:0
	ds_read_b32 v89, v115 offset:260
	ds_read_b32 v90, v115 offset:520
	ds_read_b32 v91, v115 offset:780
	ds_read_b32 v92, v115 offset:1040
	ds_read_b32 v93, v115 offset:1300
	ds_read_b32 v94, v115 offset:1560
	ds_read_b32 v95, v115 offset:1820
	ds_read_b32 v96, v115 offset:16640
	ds_read_b32 v97, v115 offset:16900
	ds_read_b32 v98, v115 offset:17160
	ds_read_b32 v99, v115 offset:17420
	ds_read_b32 v100, v115 offset:17680
	ds_read_b32 v101, v115 offset:17940
	ds_read_b32 v102, v115 offset:18200
	ds_read_b32 v103, v115 offset:18460
	s_mul_i32 s48, s85, 2
	s_add_u32 s48, s48, s86
	s_min_u32 s48, s48, s84
	s_sub_u32 s0, s48, 0xe0
	s_mul_i32 s2, s0, 0x4ed
	s_lshr_b32 s2, s2, 17
	s_mul_i32 s3, s2, 0x68
	s_sub_u32 s3, s0, s3
	s_mul_i32 s4, s2, 0x340000
	s_lshl_b32 s0, s3, 8
	s_add_u32 s4, s4, s0
	s_add_u32 s6, s80, s4
	s_addc_u32 s7, s81, 0
	s_lshl_b32 s4, s3, 17
	s_lshl_b32 s0, s2, 8
	s_add_u32 s4, s4, s0
	s_add_u32 s8, s82, s4
	s_addc_u32 s9, s83, 0
	s_movk_i32 s10, 0x6800
	s_movk_i32 s11, 0x800
	v_mul_lo_u32 v122, v116, s11
	v_add_u32_e32 v122, v122, v117
	s_waitcnt lgkmcnt(0)
	v_cvt_pk_bf16_f32 v104, v88, v89
	v_cvt_pk_bf16_f32 v105, v90, v91
	v_cvt_pk_bf16_f32 v106, v92, v93
	v_cvt_pk_bf16_f32 v107, v94, v95
	v_cvt_pk_bf16_f32 v108, v96, v97
	v_cvt_pk_bf16_f32 v109, v98, v99
	v_cvt_pk_bf16_f32 v110, v100, v101
	v_cvt_pk_bf16_f32 v111, v102, v103
	global_store_dwordx4 v122, v[104:107], s[8:9] sc1
	global_store_dwordx4 v122, v[108:111], s[8:9] offset:128 sc1
	s_nop 1
	s_waitcnt vmcnt(6)
	ds_write_b32 v114, v124 offset:33792
	ds_write_b32 v114, v125 offset:33796
	ds_write_b32 v114, v126 offset:33800
	ds_write_b32 v114, v127 offset:33804
	ds_write_b32 v114, v128 offset:42112
	ds_write_b32 v114, v129 offset:42116
	ds_write_b32 v114, v130 offset:42120
	ds_write_b32 v114, v131 offset:42124
	ds_write_b32 v114, v132 offset:50432
	ds_write_b32 v114, v133 offset:50436
	ds_write_b32 v114, v134 offset:50440
	ds_write_b32 v114, v135 offset:50444
	ds_write_b32 v114, v136 offset:58752
	ds_write_b32 v114, v137 offset:58756
	ds_write_b32 v114, v138 offset:58760
	ds_write_b32 v114, v139 offset:58764
	s_waitcnt lgkmcnt(0)
	s_barrier
	ds_read_b32 v88, v115 offset:33792
	ds_read_b32 v89, v115 offset:34052
	ds_read_b32 v90, v115 offset:34312
	ds_read_b32 v91, v115 offset:34572
	ds_read_b32 v92, v115 offset:34832
	ds_read_b32 v93, v115 offset:35092
	ds_read_b32 v94, v115 offset:35352
	ds_read_b32 v95, v115 offset:35612
	ds_read_b32 v96, v115 offset:50432
	ds_read_b32 v97, v115 offset:50692
	ds_read_b32 v98, v115 offset:50952
	ds_read_b32 v99, v115 offset:51212
	ds_read_b32 v100, v115 offset:51472
	ds_read_b32 v101, v115 offset:51732
	ds_read_b32 v102, v115 offset:51992
	ds_read_b32 v103, v115 offset:52252
	s_mul_i32 s48, s85, 3
	s_add_u32 s48, s48, s86
	s_min_u32 s48, s48, s84
	s_sub_u32 s0, s48, 0xe0
	s_mul_i32 s2, s0, 0x4ed
	s_lshr_b32 s2, s2, 17
	s_mul_i32 s3, s2, 0x68
	s_sub_u32 s3, s0, s3
	s_mul_i32 s4, s2, 0x340000
	s_lshl_b32 s0, s3, 8
	s_add_u32 s4, s4, s0
	s_add_u32 s6, s80, s4
	s_addc_u32 s7, s81, 0
	s_lshl_b32 s4, s3, 17
	s_lshl_b32 s0, s2, 8
	s_add_u32 s4, s4, s0
	s_add_u32 s8, s82, s4
	s_addc_u32 s9, s83, 0
	s_movk_i32 s10, 0x6800
	s_movk_i32 s11, 0x800
	v_mul_lo_u32 v122, v116, s11
	v_add_u32_e32 v122, v122, v117
	s_waitcnt lgkmcnt(0)
	v_cvt_pk_bf16_f32 v104, v88, v89
	v_cvt_pk_bf16_f32 v105, v90, v91
	v_cvt_pk_bf16_f32 v106, v92, v93
	v_cvt_pk_bf16_f32 v107, v94, v95
	v_cvt_pk_bf16_f32 v108, v96, v97
	v_cvt_pk_bf16_f32 v109, v98, v99
	v_cvt_pk_bf16_f32 v110, v100, v101
	v_cvt_pk_bf16_f32 v111, v102, v103
	global_store_dwordx4 v122, v[104:107], s[8:9] sc1
	global_store_dwordx4 v122, v[108:111], s[8:9] offset:128 sc1
	s_nop 1
	s_waitcnt vmcnt(0)
	s_barrier
	s_branch .LBB0_726
